# comb21 + grid barrier: the first workgroup of each XCD to arrive starts an L2 writeback early (the last arriver's release then has less to flush)
# baseline (speedup 1.0000x reference)
; __device__ __forceinline__ unsigned xb_ld(unsigned* p)              { return __hip_atomic_load(p, __ATOMIC_RELAXED, __HIP_MEMORY_SCOPE_AGENT); }
; __device__ __forceinline__ unsigned xb_add(unsigned* p, unsigned v) { return __hip_atomic_fetch_add(p, v, __ATOMIC_RELAXED, __HIP_MEMORY_SCOPE_AGENT); }
; #define XB_SPIN(cond, bar) do { unsigned _sp = 0; while (cond) { __builtin_amdgcn_s_sleep(1); \
;     if ((++_sp & 255u) == 0u) { if (xb_ld(&(bar)[XB_TMO])) break; if (_sp > XB_SPIN_CAP) { atomicAdd(&(bar)[XB_TMO], 1u); break; } } } } while (0)
; __device__ __forceinline__ void xcd_barrier(const XcdBarrier& b) {
;     ...
;         const unsigned old = xb_add(&bar[XB_XSUB(b.x)], 1u);
;         const unsigned gen = old / nloc;
;         if (old + 1u == (gen + 1u) * nloc) {
;             __builtin_amdgcn_fence(__ATOMIC_RELEASE, "agent");
;             asm volatile("s_waitcnt vmcnt(0)" ::: "memory");
;             const unsigned og = xb_add(&bar[XB_TOP], 1u);
;             const unsigned tg = og / nx;
;             if (og + 1u == (tg + 1u) * nx) xb_add(&bar[XB_TOPGEN], 1u);
;             else XB_SPIN(xb_ld(&bar[XB_TOPGEN]) == tg, bar);
;             __builtin_amdgcn_fence(__ATOMIC_ACQUIRE, "agent");
;             xb_add(&bar[XB_XGEN(b.x)], 1u);
;             asm volatile("s_waitcnt vmcnt(0)" ::: "memory");
;         } else {
;             XB_SPIN(xb_ld(&bar[XB_XGEN(b.x)]) == gen, bar);
;             __builtin_amdgcn_fence(__ATOMIC_ACQUIRE, "agent");
;             asm volatile("s_waitcnt vmcnt(0)" ::: "memory");
;         }
.LBB0_103:
	v_readlane_b32 s4, v248, 10
	s_lshl_b32 s4, s4, 8
	v_readlane_b32 s6, v248, 8
	v_readlane_b32 s7, v248, 9
	s_add_u32 s4, s6, s4
	s_addc_u32 s5, s7, 0
	v_mov_b32_e32 v2, 0x1000
	v_mov_b32_e32 v4, 1
	global_atomic_add v4, v2, v4, s[4:5] offset:1024 sc0
	v_cvt_f32_u32_e32 v2, v3
	v_sub_u32_e32 v5, 0, v3
	v_rcp_iflag_f32_e32 v2, v2
	s_nop 0
	v_mul_f32_e32 v2, 0x4f7ffffe, v2
	v_cvt_u32_f32_e32 v2, v2
	v_mul_lo_u32 v5, v5, v2
	v_mul_hi_u32 v5, v2, v5
	v_add_u32_e32 v2, v2, v5
	s_waitcnt vmcnt(0)
	v_mul_hi_u32 v2, v4, v2
	v_mul_lo_u32 v5, v2, v3
	v_sub_u32_e32 v5, v4, v5
	v_add_u32_e32 v6, 1, v2
	v_cmp_ge_u32_e32 vcc, v5, v3
	v_add_u32_e32 v4, 1, v4
	s_nop 0
	v_cndmask_b32_e32 v2, v2, v6, vcc
	v_sub_u32_e32 v6, v5, v3
	v_cndmask_b32_e32 v5, v5, v6, vcc
	v_add_u32_e32 v6, 1, v2
	v_cmp_ge_u32_e32 vcc, v5, v3
	s_nop 1
	v_cndmask_b32_e32 v2, v2, v6, vcc
	v_mul_lo_u32 v5, v3, v2
	v_add_u32_e32 v3, v5, v3
	v_cmp_ne_u32_e32 vcc, v4, v3
	s_and_saveexec_b64 s[6:7], vcc
	s_xor_b64 s[6:7], exec, s[6:7]
	s_cbranch_execz .LBB0_117
	s_waitcnt lgkmcnt(0)
	buffer_inv sc1
	v_add_u32_e32 v249, 1, v5
	v_cmp_eq_u32_e32 vcc, v4, v249
	s_and_saveexec_b64 s[98:99], vcc
	s_cbranch_execz .Lfw_0
	buffer_wbl2 sc1
.Lfw_0:
	s_or_b64 exec, exec, s[98:99]
	v_mov_b32_e32 v1, 0x2000
	global_load_dword v1, v1, s[4:5] offset:1024 sc1
	s_add_u32 s14, s4, 0x2400
	s_addc_u32 s15, s5, 0
	s_waitcnt vmcnt(0)
	v_cmp_eq_u32_e32 vcc, v1, v2
	s_and_saveexec_b64 s[8:9], vcc
	s_cbranch_execz .LBB0_116
	s_add_u32 s12, s30, 0x3f52c200
	s_addc_u32 s13, s31, 0
	s_mov_b32 s27, 1
	s_mov_b64 s[16:17], 0
	v_mov_b32_e32 v1, 0
	s_branch .LBB0_107

; __device__ __forceinline__ unsigned xb_ld(unsigned* p)              { return __hip_atomic_load(p, __ATOMIC_RELAXED, __HIP_MEMORY_SCOPE_AGENT); }
; __device__ __forceinline__ unsigned xb_add(unsigned* p, unsigned v) { return __hip_atomic_fetch_add(p, v, __ATOMIC_RELAXED, __HIP_MEMORY_SCOPE_AGENT); }
; #define XB_SPIN(cond, bar) do { unsigned _sp = 0; while (cond) { __builtin_amdgcn_s_sleep(1); \
;     if ((++_sp & 255u) == 0u) { if (xb_ld(&(bar)[XB_TMO])) break; if (_sp > XB_SPIN_CAP) { atomicAdd(&(bar)[XB_TMO], 1u); break; } } } } while (0)
; __device__ __forceinline__ void xcd_barrier(const XcdBarrier& b) {
;     ...
;         const unsigned old = xb_add(&bar[XB_XSUB(b.x)], 1u);
;         const unsigned gen = old / nloc;
;         if (old + 1u == (gen + 1u) * nloc) {
;             __builtin_amdgcn_fence(__ATOMIC_RELEASE, "agent");
;             asm volatile("s_waitcnt vmcnt(0)" ::: "memory");
;             const unsigned og = xb_add(&bar[XB_TOP], 1u);
;             const unsigned tg = og / nx;
;             if (og + 1u == (tg + 1u) * nx) xb_add(&bar[XB_TOPGEN], 1u);
;             else XB_SPIN(xb_ld(&bar[XB_TOPGEN]) == tg, bar);
;             __builtin_amdgcn_fence(__ATOMIC_ACQUIRE, "agent");
;             xb_add(&bar[XB_XGEN(b.x)], 1u);
;             asm volatile("s_waitcnt vmcnt(0)" ::: "memory");
;         } else {
;             XB_SPIN(xb_ld(&bar[XB_XGEN(b.x)]) == gen, bar);
;             __builtin_amdgcn_fence(__ATOMIC_ACQUIRE, "agent");
;             asm volatile("s_waitcnt vmcnt(0)" ::: "memory");
;         }
.LBB0_175:
	v_readlane_b32 s4, v248, 10
	s_lshl_b32 s4, s4, 8
	v_readlane_b32 s8, v248, 8
	v_readlane_b32 s9, v248, 9
	s_add_u32 s4, s8, s4
	s_addc_u32 s5, s9, 0
	v_mov_b32_e32 v3, 0x1000
	v_mov_b32_e32 v5, 1
	global_atomic_add v5, v3, v5, s[4:5] offset:1024 sc0
	v_cvt_f32_u32_e32 v3, v4
	v_sub_u32_e32 v6, 0, v4
	v_rcp_iflag_f32_e32 v3, v3
	s_nop 0
	v_mul_f32_e32 v3, 0x4f7ffffe, v3
	v_cvt_u32_f32_e32 v3, v3
	v_mul_lo_u32 v6, v6, v3
	v_mul_hi_u32 v6, v3, v6
	v_add_u32_e32 v3, v3, v6
	s_waitcnt vmcnt(0)
	v_mul_hi_u32 v3, v5, v3
	v_mul_lo_u32 v6, v3, v4
	v_sub_u32_e32 v6, v5, v6
	v_add_u32_e32 v7, 1, v3
	v_cmp_ge_u32_e32 vcc, v6, v4
	v_add_u32_e32 v5, 1, v5
	s_nop 0
	v_cndmask_b32_e32 v3, v3, v7, vcc
	v_sub_u32_e32 v7, v6, v4
	v_cndmask_b32_e32 v6, v6, v7, vcc
	v_add_u32_e32 v7, 1, v3
	v_cmp_ge_u32_e32 vcc, v6, v4
	s_nop 1
	v_cndmask_b32_e32 v3, v3, v7, vcc
	v_mul_lo_u32 v6, v4, v3
	v_add_u32_e32 v4, v6, v4
	v_cmp_ne_u32_e32 vcc, v5, v4
	s_and_saveexec_b64 s[8:9], vcc
	s_xor_b64 s[8:9], exec, s[8:9]
	s_cbranch_execz .LBB0_189
	s_waitcnt lgkmcnt(0)
	buffer_inv sc1
	v_add_u32_e32 v249, 1, v6
	v_cmp_eq_u32_e32 vcc, v5, v249
	s_and_saveexec_b64 s[98:99], vcc
	s_cbranch_execz .Lfw_1
	buffer_wbl2 sc1
.Lfw_1:
	s_or_b64 exec, exec, s[98:99]
	v_mov_b32_e32 v2, 0x2000
	global_load_dword v2, v2, s[4:5] offset:1024 sc1
	s_add_u32 s14, s4, 0x2400
	s_addc_u32 s15, s5, 0
	s_waitcnt vmcnt(0)
	v_cmp_eq_u32_e32 vcc, v2, v3
	s_and_saveexec_b64 s[10:11], vcc
	s_cbranch_execz .LBB0_188
	s_add_u32 s12, s30, 0x3f52c200
	s_addc_u32 s13, s31, 0
	s_mov_b32 s27, 1
	s_mov_b64 s[16:17], 0
	v_mov_b32_e32 v2, 0
	s_branch .LBB0_179

; __device__ __forceinline__ unsigned xb_ld(unsigned* p)              { return __hip_atomic_load(p, __ATOMIC_RELAXED, __HIP_MEMORY_SCOPE_AGENT); }
; __device__ __forceinline__ unsigned xb_add(unsigned* p, unsigned v) { return __hip_atomic_fetch_add(p, v, __ATOMIC_RELAXED, __HIP_MEMORY_SCOPE_AGENT); }
; #define XB_SPIN(cond, bar) do { unsigned _sp = 0; while (cond) { __builtin_amdgcn_s_sleep(1); \
;     if ((++_sp & 255u) == 0u) { if (xb_ld(&(bar)[XB_TMO])) break; if (_sp > XB_SPIN_CAP) { atomicAdd(&(bar)[XB_TMO], 1u); break; } } } } while (0)
; __device__ __forceinline__ void xcd_barrier(const XcdBarrier& b) {
;     ...
;         const unsigned old = xb_add(&bar[XB_XSUB(b.x)], 1u);
;         const unsigned gen = old / nloc;
;         if (old + 1u == (gen + 1u) * nloc) {
;             __builtin_amdgcn_fence(__ATOMIC_RELEASE, "agent");
;             asm volatile("s_waitcnt vmcnt(0)" ::: "memory");
;             const unsigned og = xb_add(&bar[XB_TOP], 1u);
;             const unsigned tg = og / nx;
;             if (og + 1u == (tg + 1u) * nx) xb_add(&bar[XB_TOPGEN], 1u);
;             else XB_SPIN(xb_ld(&bar[XB_TOPGEN]) == tg, bar);
;             __builtin_amdgcn_fence(__ATOMIC_ACQUIRE, "agent");
;             xb_add(&bar[XB_XGEN(b.x)], 1u);
;             asm volatile("s_waitcnt vmcnt(0)" ::: "memory");
;         } else {
;             XB_SPIN(xb_ld(&bar[XB_XGEN(b.x)]) == gen, bar);
.LBB0_308:
	v_readlane_b32 s4, v248, 10
	s_lshl_b32 s4, s4, 8
	v_readlane_b32 s6, v248, 8
	v_readlane_b32 s7, v248, 9
	s_add_u32 s4, s6, s4
	s_addc_u32 s5, s7, 0
	v_mov_b32_e32 v3, 0x1000
	v_mov_b32_e32 v5, 1
	global_atomic_add v5, v3, v5, s[4:5] offset:1024 sc0
	v_cvt_f32_u32_e32 v3, v4
	v_sub_u32_e32 v6, 0, v4
	v_rcp_iflag_f32_e32 v3, v3
	s_nop 0
	v_mul_f32_e32 v3, 0x4f7ffffe, v3
	v_cvt_u32_f32_e32 v3, v3
	v_mul_lo_u32 v6, v6, v3
	v_mul_hi_u32 v6, v3, v6
	v_add_u32_e32 v3, v3, v6
	s_waitcnt vmcnt(0)
	v_mul_hi_u32 v3, v5, v3
	v_mul_lo_u32 v6, v3, v4
	v_sub_u32_e32 v6, v5, v6
	v_add_u32_e32 v7, 1, v3
	v_cmp_ge_u32_e32 vcc, v6, v4
	v_add_u32_e32 v5, 1, v5
	s_nop 0
	v_cndmask_b32_e32 v3, v3, v7, vcc
	v_sub_u32_e32 v7, v6, v4
	v_cndmask_b32_e32 v6, v6, v7, vcc
	v_add_u32_e32 v7, 1, v3
	v_cmp_ge_u32_e32 vcc, v6, v4
	s_nop 1
	v_cndmask_b32_e32 v3, v3, v7, vcc
	v_mul_lo_u32 v6, v4, v3
	v_add_u32_e32 v4, v6, v4
	v_cmp_ne_u32_e32 vcc, v5, v4
	s_and_saveexec_b64 s[6:7], vcc
	s_xor_b64 s[6:7], exec, s[6:7]
	s_cbranch_execz .LBB0_322
	s_waitcnt lgkmcnt(0)
	buffer_inv sc1
	v_add_u32_e32 v249, 1, v6
	v_cmp_eq_u32_e32 vcc, v5, v249
	s_and_saveexec_b64 s[98:99], vcc
	s_cbranch_execz .Lfw_2
	buffer_wbl2 sc1

; __device__ __forceinline__ unsigned xb_ld(unsigned* p)              { return __hip_atomic_load(p, __ATOMIC_RELAXED, __HIP_MEMORY_SCOPE_AGENT); }
; #define XB_SPIN(cond, bar) do { unsigned _sp = 0; while (cond) { __builtin_amdgcn_s_sleep(1); \
;     if ((++_sp & 255u) == 0u) { if (xb_ld(&(bar)[XB_TMO])) break; if (_sp > XB_SPIN_CAP) { atomicAdd(&(bar)[XB_TMO], 1u); break; } } } } while (0)
; __device__ __forceinline__ void xcd_barrier(const XcdBarrier& b) {
;     ...
;             XB_SPIN(xb_ld(&bar[XB_XGEN(b.x)]) == gen, bar);
;             __builtin_amdgcn_fence(__ATOMIC_ACQUIRE, "agent");
.Lfw_3:
	s_or_b64 exec, exec, s[98:99]
	v_mov_b32_e32 v2, 0x2000
	global_load_dword v2, v2, s[4:5] offset:1024 sc1
	s_add_u32 s12, s4, 0x2400
	s_addc_u32 s13, s5, 0
	s_waitcnt vmcnt(0)
	v_cmp_eq_u32_e32 vcc, v2, v3
	s_and_saveexec_b64 s[8:9], vcc
	s_cbranch_execz .LBB0_719
	s_add_u32 s10, s30, 0x3f52c200
	s_addc_u32 s11, s31, 0
	s_mov_b32 s24, 1
	s_mov_b64 s[14:15], 0
	v_mov_b32_e32 v2, 0
	s_branch .LBB0_710

; __device__ __forceinline__ unsigned xb_ld(unsigned* p)              { return __hip_atomic_load(p, __ATOMIC_RELAXED, __HIP_MEMORY_SCOPE_AGENT); }
; #define XB_SPIN(cond, bar) do { unsigned _sp = 0; while (cond) { __builtin_amdgcn_s_sleep(1); \
;     if ((++_sp & 255u) == 0u) { if (xb_ld(&(bar)[XB_TMO])) break; if (_sp > XB_SPIN_CAP) { atomicAdd(&(bar)[XB_TMO], 1u); break; } } } } while (0)
; __device__ __forceinline__ void xcd_barrier(const XcdBarrier& b) {
;     ...
;             XB_SPIN(xb_ld(&bar[XB_XGEN(b.x)]) == gen, bar);
;             __builtin_amdgcn_fence(__ATOMIC_ACQUIRE, "agent");
.Lfw_4:
	s_or_b64 exec, exec, s[98:99]
	v_mov_b32_e32 v2, 0x2000
	global_load_dword v2, v2, s[4:5] offset:1024 sc1
	s_add_u32 s12, s4, 0x2400
	s_addc_u32 s13, s5, 0
	s_waitcnt vmcnt(0)
	v_cmp_eq_u32_e32 vcc, v2, v3
	s_and_saveexec_b64 s[8:9], vcc
	s_cbranch_execz .LBB0_858
	s_add_u32 s10, s30, 0x3f52c200
	s_addc_u32 s11, s31, 0
	s_mov_b32 s27, 1
	s_mov_b64 s[14:15], 0
	v_mov_b32_e32 v2, 0
	s_branch .LBB0_849

; __device__ __forceinline__ unsigned xb_ld(unsigned* p)              { return __hip_atomic_load(p, __ATOMIC_RELAXED, __HIP_MEMORY_SCOPE_AGENT); }
; __device__ __forceinline__ unsigned xb_add(unsigned* p, unsigned v) { return __hip_atomic_fetch_add(p, v, __ATOMIC_RELAXED, __HIP_MEMORY_SCOPE_AGENT); }
; #define XB_SPIN(cond, bar) do { unsigned _sp = 0; while (cond) { __builtin_amdgcn_s_sleep(1); \
;     if ((++_sp & 255u) == 0u) { if (xb_ld(&(bar)[XB_TMO])) break; if (_sp > XB_SPIN_CAP) { atomicAdd(&(bar)[XB_TMO], 1u); break; } } } } while (0)
; __device__ __forceinline__ void xcd_barrier(const XcdBarrier& b) {
;     ...
;         const unsigned old = xb_add(&bar[XB_XSUB(b.x)], 1u);
;         const unsigned gen = old / nloc;
;         if (old + 1u == (gen + 1u) * nloc) {
;             __builtin_amdgcn_fence(__ATOMIC_RELEASE, "agent");
;             asm volatile("s_waitcnt vmcnt(0)" ::: "memory");
;             const unsigned og = xb_add(&bar[XB_TOP], 1u);
;             const unsigned tg = og / nx;
;             if (og + 1u == (tg + 1u) * nx) xb_add(&bar[XB_TOPGEN], 1u);
;             else XB_SPIN(xb_ld(&bar[XB_TOPGEN]) == tg, bar);
;             __builtin_amdgcn_fence(__ATOMIC_ACQUIRE, "agent");
;             xb_add(&bar[XB_XGEN(b.x)], 1u);
;             asm volatile("s_waitcnt vmcnt(0)" ::: "memory");
;         } else {
;             XB_SPIN(xb_ld(&bar[XB_XGEN(b.x)]) == gen, bar);
;             __builtin_amdgcn_fence(__ATOMIC_ACQUIRE, "agent");
;             asm volatile("s_waitcnt vmcnt(0)" ::: "memory");
;         }
.LBB0_2262:
	v_readlane_b32 s2, v248, 10
	s_lshl_b32 s2, s2, 8
	v_readlane_b32 s4, v248, 8
	v_readlane_b32 s5, v248, 9
	s_add_u32 s2, s4, s2
	s_addc_u32 s3, s5, 0
	v_mov_b32_e32 v3, 0x1000
	v_mov_b32_e32 v5, 1
	global_atomic_add v5, v3, v5, s[2:3] offset:1024 sc0
	v_cvt_f32_u32_e32 v3, v4
	v_sub_u32_e32 v6, 0, v4
	v_rcp_iflag_f32_e32 v3, v3
	s_nop 0
	v_mul_f32_e32 v3, 0x4f7ffffe, v3
	v_cvt_u32_f32_e32 v3, v3
	v_mul_lo_u32 v6, v6, v3
	v_mul_hi_u32 v6, v3, v6
	v_add_u32_e32 v3, v3, v6
	s_waitcnt vmcnt(0)
	v_mul_hi_u32 v3, v5, v3
	v_mul_lo_u32 v6, v3, v4
	v_sub_u32_e32 v6, v5, v6
	v_add_u32_e32 v7, 1, v3
	v_cmp_ge_u32_e32 vcc, v6, v4
	v_add_u32_e32 v5, 1, v5
	s_nop 0
	v_cndmask_b32_e32 v3, v3, v7, vcc
	v_sub_u32_e32 v7, v6, v4
	v_cndmask_b32_e32 v6, v6, v7, vcc
	v_add_u32_e32 v7, 1, v3
	v_cmp_ge_u32_e32 vcc, v6, v4
	s_nop 1
	v_cndmask_b32_e32 v3, v3, v7, vcc
	v_mul_lo_u32 v6, v4, v3
	v_add_u32_e32 v4, v6, v4
	v_cmp_ne_u32_e32 vcc, v5, v4
	s_and_saveexec_b64 s[4:5], vcc
	s_xor_b64 s[4:5], exec, s[4:5]
	s_cbranch_execz .LBB0_2276
	s_waitcnt lgkmcnt(0)
	buffer_inv sc1
	v_add_u32_e32 v249, 1, v6
	v_cmp_eq_u32_e32 vcc, v5, v249
	s_and_saveexec_b64 s[98:99], vcc
	s_cbranch_execz .Lfw_17
	buffer_wbl2 sc1
.Lfw_17:
	s_or_b64 exec, exec, s[98:99]
	v_mov_b32_e32 v2, 0x2000
	global_load_dword v2, v2, s[2:3] offset:1024 sc1
	s_add_u32 s12, s2, 0x2400
	s_addc_u32 s13, s3, 0
	s_waitcnt vmcnt(0)
	v_cmp_eq_u32_e32 vcc, v2, v3
	s_and_saveexec_b64 s[8:9], vcc
	s_cbranch_execz .LBB0_2275
	s_add_u32 s10, s30, 0x3f52c200
	s_addc_u32 s11, s31, 0
	s_mov_b32 s24, 1
	s_mov_b64 s[14:15], 0
	v_mov_b32_e32 v2, 0
	s_branch .LBB0_2266
